# attention map-1: LDS fragment reads for QK block 1 and the first PV operands issued ahead of the exp/cvt phase (counted lgkmcnt re-derived); otherwise as v60
# speedup vs baseline: 1.0061x; 1.0061x over previous
.LBB0_290:
	s_add_i32 s54, s55, 1
	s_cmp_lt_u32 s54, s51
	s_cselect_b32 s56, s54, s16
	v_lshl_add_u32 v128, s56, 17, v242
	v_lshl_add_u32 v129, s56, 7, v243
	v_add_u32_e32 v130, 0x10000, v128
	global_load_dwordx4 v[152:155], v128, s[4:5]
	global_load_dwordx4 v[148:151], v129, s[6:7]
	v_add_u32_e32 v128, 0x80000, v129
	global_load_dwordx4 v[156:159], v130, s[4:5]
	global_load_dwordx4 v[144:147], v128, s[6:7]
	s_bitcmp1_b32 s55, 0
	s_cselect_b32 s55, 0x9000, 0
	v_add_u32_e32 v247, s55, v245
	ds_read_b128 v[128:131], v247
	ds_read_b128 v[160:163], v247 offset:32
	ds_read_b128 v[132:135], v246
	ds_read_b128 v[164:167], v246 offset:32
	ds_read_b128 v[172:175], v247 offset:64
	ds_read_b128 v[176:179], v246 offset:64
	s_waitcnt lgkmcnt(3)
	v_mfma_f32_32x32x16_bf16 v[128:143], v[128:131], v[132:135], 0
	s_waitcnt lgkmcnt(2)
	v_mfma_f32_32x32x16_bf16 v[128:143], v[160:163], v[164:167], v[128:143]
	ds_read_b128 v[160:163], v247 offset:96
	ds_read_b128 v[164:167], v246 offset:96
	s_waitcnt lgkmcnt(2)
	v_mfma_f32_32x32x16_bf16 v[128:143], v[172:175], v[176:179], v[128:143]
	s_waitcnt lgkmcnt(0)
	v_mfma_f32_32x32x16_bf16 v[128:143], v[160:163], v[164:167], v[128:143]
	ds_read_b128 v[180:183], v247 offset:4640
	ds_read_b128 v[184:187], v246 offset:32
	ds_read_b128 v[188:191], v247 offset:4672
	ds_read_b128 v[192:195], v246 offset:64
	s_nop 8
	v_exp_f32_e32 v164, v128
	v_exp_f32_e32 v226, v129
	v_exp_f32_e32 v160, v130
	v_exp_f32_e32 v224, v131
	ds_read_b128 v[128:131], v247 offset:4608
	v_exp_f32_e32 v166, v132
	v_exp_f32_e32 v222, v133
	v_exp_f32_e32 v162, v134
	v_exp_f32_e32 v220, v135
	ds_read_b128 v[132:135], v246
	v_exp_f32_e32 v218, v136
	v_exp_f32_e32 v214, v137
	v_exp_f32_e32 v212, v138
	v_exp_f32_e32 v210, v139
	v_exp_f32_e32 v178, v140
	v_exp_f32_e32 v176, v141
	v_exp_f32_e32 v174, v142
	v_exp_f32_e32 v172, v143
	v_cvt_pk_bf16_f32 v248, v164, v226
	v_cvt_pk_bf16_f32 v234, v218, v214
	v_cvt_pk_bf16_f32 v249, v160, v224
	v_cvt_pk_bf16_f32 v235, v212, v210
	v_cvt_pk_bf16_f32 v250, v166, v222
	v_cvt_pk_bf16_f32 v236, v178, v176
	v_cvt_pk_bf16_f32 v251, v162, v220
	v_cvt_pk_bf16_f32 v237, v174, v172
	s_waitcnt lgkmcnt(0)
	v_mfma_f32_32x32x16_bf16 v[128:143], v[128:131], v[132:135], 0
	s_waitcnt lgkmcnt(2)
	v_mfma_f32_32x32x16_bf16 v[128:143], v[180:183], v[184:187], v[128:143]
	ds_read_b128 v[180:183], v247 offset:4704
	ds_read_b128 v[184:187], v246 offset:96
	s_waitcnt lgkmcnt(2)
	v_mfma_f32_32x32x16_bf16 v[128:143], v[188:191], v[192:195], v[128:143]
	s_waitcnt lgkmcnt(0)
	v_mfma_f32_32x32x16_bf16 v[128:143], v[180:183], v[184:187], v[128:143]
	ds_read_b128 v[228:231], v247 offset:18496
	ds_read_b128 v[238:241], v247 offset:18528
	s_nop 10
	v_exp_f32_e32 v216, v128
	v_exp_f32_e32 v208, v129
	v_exp_f32_e32 v206, v130
	v_exp_f32_e32 v204, v131
	v_exp_f32_e32 v202, v132
	v_exp_f32_e32 v200, v133
	v_exp_f32_e32 v198, v134
	v_exp_f32_e32 v196, v135
	v_exp_f32_e32 v194, v136
	v_exp_f32_e32 v192, v137
	v_exp_f32_e32 v190, v138
	v_exp_f32_e32 v188, v139
	ds_read_b128 v[136:139], v247 offset:18432
	v_exp_f32_e32 v186, v140
	v_exp_f32_e32 v184, v141
	v_exp_f32_e32 v182, v142
	v_exp_f32_e32 v180, v143
	ds_read_b128 v[140:143], v247 offset:18464
	v_cvt_pk_bf16_f32 v128, v216, v208
	v_cvt_pk_bf16_f32 v132, v194, v192
	v_cvt_pk_bf16_f32 v129, v206, v204
	v_cvt_pk_bf16_f32 v133, v190, v188
	v_cvt_pk_bf16_f32 v130, v202, v200
	v_cvt_pk_bf16_f32 v134, v186, v184
	v_cvt_pk_bf16_f32 v131, v198, v196
	v_cvt_pk_bf16_f32 v135, v182, v180
	s_waitcnt lgkmcnt(1)
	v_mfma_f32_32x32x16_bf16 v[32:47], v[248:251], v[136:139], v[32:47]
	ds_read_b128 v[136:139], v247 offset:23040
	s_waitcnt lgkmcnt(1)
	v_mfma_f32_32x32x16_bf16 v[32:47], v[234:237], v[140:143], v[32:47]
	ds_read_b128 v[140:143], v247 offset:23072
	s_waitcnt lgkmcnt(3)
	v_mfma_f32_32x32x16_bf16 v[32:47], v[128:131], v[228:231], v[32:47]
	ds_read_b128 v[228:231], v247 offset:23104
	s_waitcnt lgkmcnt(3)
	v_mfma_f32_32x32x16_bf16 v[32:47], v[132:135], v[238:241], v[32:47]
	ds_read_b128 v[238:241], v247 offset:23136
	s_waitcnt lgkmcnt(3)
	v_mfma_f32_32x32x16_bf16 v[112:127], v[248:251], v[136:139], v[112:127]
	ds_read_b128 v[136:139], v247 offset:27648
	s_waitcnt lgkmcnt(3)
	v_mfma_f32_32x32x16_bf16 v[112:127], v[234:237], v[140:143], v[112:127]
	ds_read_b128 v[140:143], v247 offset:27680
	s_waitcnt lgkmcnt(3)
	v_mfma_f32_32x32x16_bf16 v[112:127], v[128:131], v[228:231], v[112:127]
	ds_read_b128 v[228:231], v247 offset:27712
	s_waitcnt lgkmcnt(3)
	v_mfma_f32_32x32x16_bf16 v[112:127], v[132:135], v[238:241], v[112:127]
	ds_read_b128 v[238:241], v247 offset:27744
	s_waitcnt lgkmcnt(3)
	v_mfma_f32_32x32x16_bf16 v[64:79], v[248:251], v[136:139], v[64:79]
	ds_read_b128 v[136:139], v247 offset:32256
	s_waitcnt lgkmcnt(3)
	v_mfma_f32_32x32x16_bf16 v[64:79], v[234:237], v[140:143], v[64:79]
	ds_read_b128 v[140:143], v247 offset:32288
	s_waitcnt lgkmcnt(3)
	v_mfma_f32_32x32x16_bf16 v[64:79], v[128:131], v[228:231], v[64:79]
	ds_read_b128 v[228:231], v247 offset:32320
	s_waitcnt lgkmcnt(3)
	v_mfma_f32_32x32x16_bf16 v[64:79], v[132:135], v[238:241], v[64:79]
	ds_read_b128 v[238:241], v247 offset:32352
	s_waitcnt lgkmcnt(3)
	v_mfma_f32_32x32x16_bf16 v[0:15], v[248:251], v[136:139], v[0:15]
	s_waitcnt lgkmcnt(2)
	v_mfma_f32_32x32x16_bf16 v[0:15], v[234:237], v[140:143], v[0:15]
	s_waitcnt lgkmcnt(1)
	v_mfma_f32_32x32x16_bf16 v[0:15], v[128:131], v[228:231], v[0:15]
	s_waitcnt lgkmcnt(0)
	v_mfma_f32_32x32x16_bf16 v[0:15], v[132:135], v[238:241], v[0:15]
	ds_read_b128 v[128:131], v247 offset:9216
	ds_read_b128 v[228:231], v247 offset:9248
	ds_read_b128 v[132:135], v246 offset:128
	ds_read_b128 v[234:237], v246 offset:160
	ds_read_b128 v[238:241], v247 offset:9280
	ds_read_b128 v[248:251], v246 offset:192
	s_waitcnt lgkmcnt(3)
	v_mfma_f32_32x32x16_bf16 v[128:143], v[128:131], v[132:135], 0
	s_waitcnt lgkmcnt(2)
	v_mfma_f32_32x32x16_bf16 v[128:143], v[228:231], v[234:237], v[128:143]
	ds_read_b128 v[228:231], v247 offset:9312
	ds_read_b128 v[234:237], v246 offset:224
	s_waitcnt lgkmcnt(2)
	v_mfma_f32_32x32x16_bf16 v[128:143], v[238:241], v[248:251], v[128:143]
	s_waitcnt lgkmcnt(0)
	v_mfma_f32_32x32x16_bf16 v[128:143], v[228:231], v[234:237], v[128:143]
	s_nop 11
	v_exp_f32_e32 v165, v128
	v_exp_f32_e32 v227, v129
	v_exp_f32_e32 v161, v130
	v_exp_f32_e32 v225, v131
	v_exp_f32_e32 v167, v132
	v_pk_add_f32 v[128:129], v[164:165], 0 op_sel_hi:[1,0]
	v_exp_f32_e32 v223, v133
	v_pk_add_f32 v[128:129], v[226:227], v[128:129]
	v_exp_f32_e32 v163, v134
	v_pk_add_f32 v[128:129], v[160:161], v[128:129]
	v_exp_f32_e32 v221, v135
	v_pk_add_f32 v[128:129], v[224:225], v[128:129]
	v_exp_f32_e32 v219, v136
	v_pk_add_f32 v[128:129], v[166:167], v[128:129]
	v_exp_f32_e32 v215, v137
	v_pk_add_f32 v[128:129], v[222:223], v[128:129]
	v_exp_f32_e32 v213, v138
	v_pk_add_f32 v[230:231], v[162:163], v[128:129]
	v_exp_f32_e32 v211, v139
	v_exp_f32_e32 v179, v140
	v_exp_f32_e32 v177, v141
	v_exp_f32_e32 v175, v142
	v_exp_f32_e32 v173, v143
	v_cvt_pk_bf16_f32 v164, v165, v227
	v_cvt_pk_bf16_f32 v160, v219, v215
	v_cvt_pk_bf16_f32 v165, v161, v225
	v_cvt_pk_bf16_f32 v161, v213, v211
	v_cvt_pk_bf16_f32 v166, v167, v223
	v_cvt_pk_bf16_f32 v162, v179, v177
	v_cvt_pk_bf16_f32 v167, v163, v221
	v_cvt_pk_bf16_f32 v163, v175, v173
	ds_read_b128 v[128:131], v247 offset:13824
	ds_read_b128 v[222:225], v247 offset:13856
	ds_read_b128 v[132:135], v246 offset:128
	ds_read_b128 v[226:229], v246 offset:160
	ds_read_b128 v[234:237], v247 offset:13888
	ds_read_b128 v[238:241], v246 offset:192
	s_waitcnt lgkmcnt(3)
	v_mfma_f32_32x32x16_bf16 v[128:143], v[128:131], v[132:135], 0
	s_waitcnt lgkmcnt(2)
	v_mfma_f32_32x32x16_bf16 v[128:143], v[222:225], v[226:229], v[128:143]
	ds_read_b128 v[222:225], v247 offset:13920
	ds_read_b128 v[226:229], v246 offset:224
	s_waitcnt lgkmcnt(2)
	v_mfma_f32_32x32x16_bf16 v[128:143], v[234:237], v[238:241], v[128:143]
	s_waitcnt lgkmcnt(0)
	v_mfma_f32_32x32x16_bf16 v[128:143], v[222:225], v[226:229], v[128:143]
	s_nop 11
	v_exp_f32_e32 v217, v128
	v_exp_f32_e32 v209, v129
	v_exp_f32_e32 v207, v130
	v_exp_f32_e32 v205, v131
	v_exp_f32_e32 v203, v132
	v_exp_f32_e32 v195, v136
	v_exp_f32_e32 v193, v137
	v_pk_add_f32 v[136:137], v[216:217], 0 op_sel_hi:[1,0]
	v_exp_f32_e32 v201, v133
	v_pk_add_f32 v[136:137], v[208:209], v[136:137]
	v_exp_f32_e32 v199, v134
	v_pk_add_f32 v[136:137], v[206:207], v[136:137]
	v_exp_f32_e32 v197, v135
	v_pk_add_f32 v[136:137], v[204:205], v[136:137]
	v_exp_f32_e32 v191, v138
	v_pk_add_f32 v[136:137], v[202:203], v[136:137]
	v_pk_add_f32 v[128:129], v[220:221], v[230:231]
	v_pk_add_f32 v[136:137], v[200:201], v[136:137]
	v_exp_f32_e32 v189, v139
	v_pk_add_f32 v[136:137], v[198:199], v[136:137]
	v_pk_add_f32 v[128:129], v[218:219], v[128:129]
	v_pk_add_f32 v[136:137], v[196:197], v[136:137]
	v_exp_f32_e32 v187, v140
	v_pk_add_f32 v[128:129], v[214:215], v[128:129]
	v_pk_add_f32 v[136:137], v[194:195], v[136:137]
	v_exp_f32_e32 v185, v141
	v_pk_add_f32 v[128:129], v[212:213], v[128:129]
	v_pk_add_f32 v[136:137], v[192:193], v[136:137]
	v_exp_f32_e32 v183, v142
	v_pk_add_f32 v[138:139], v[210:211], v[128:129]
	v_pk_add_f32 v[136:137], v[190:191], v[136:137]
	v_exp_f32_e32 v181, v143
	v_pk_add_f32 v[138:139], v[178:179], v[138:139]
	v_pk_add_f32 v[136:137], v[188:189], v[136:137]
	v_pk_add_f32 v[138:139], v[176:177], v[138:139]
	v_pk_add_f32 v[136:137], v[186:187], v[136:137]
	v_pk_add_f32 v[138:139], v[174:175], v[138:139]
	v_pk_add_f32 v[136:137], v[184:185], v[136:137]
	v_pk_add_f32 v[138:139], v[172:173], v[138:139]
	v_pk_add_f32 v[136:137], v[182:183], v[136:137]
	v_pk_add_f32 v[138:139], v[170:171], v[138:139]
	v_pk_add_f32 v[136:137], v[180:181], v[136:137]
	v_cvt_pk_bf16_f32 v128, v217, v209
	v_cvt_pk_bf16_f32 v132, v195, v193
	v_cvt_pk_bf16_f32 v129, v207, v205
	v_cvt_pk_bf16_f32 v133, v191, v189
	v_cvt_pk_bf16_f32 v130, v203, v201
	s_nop 0
	v_pk_add_f32 v[170:171], v[138:139], v[136:137]
	v_cvt_pk_bf16_f32 v134, v187, v185
	v_cvt_pk_bf16_f32 v131, v199, v197
	v_cvt_pk_bf16_f32 v135, v183, v181
	ds_read_b128 v[136:139], v247 offset:18432
	ds_read_b128 v[140:143], v247 offset:18464
	ds_read_b128 v[172:175], v247 offset:18496
	ds_read_b128 v[176:179], v247 offset:18528
	s_waitcnt lgkmcnt(3)
	v_mfma_f32_32x32x16_bf16 v[96:111], v[164:167], v[136:139], v[96:111]
	ds_read_b128 v[136:139], v247 offset:23040
	s_waitcnt lgkmcnt(3)
	v_mfma_f32_32x32x16_bf16 v[96:111], v[160:163], v[140:143], v[96:111]
	ds_read_b128 v[140:143], v247 offset:23072
	s_waitcnt lgkmcnt(3)
	v_mfma_f32_32x32x16_bf16 v[96:111], v[128:131], v[172:175], v[96:111]
	ds_read_b128 v[172:175], v247 offset:23104
	s_waitcnt lgkmcnt(3)
	v_mfma_f32_32x32x16_bf16 v[96:111], v[132:135], v[176:179], v[96:111]
	ds_read_b128 v[176:179], v247 offset:23136
	s_waitcnt lgkmcnt(3)
	v_mfma_f32_32x32x16_bf16 v[80:95], v[164:167], v[136:139], v[80:95]
	ds_read_b128 v[136:139], v247 offset:27648
	s_waitcnt lgkmcnt(3)
	v_mfma_f32_32x32x16_bf16 v[80:95], v[160:163], v[140:143], v[80:95]
	ds_read_b128 v[140:143], v247 offset:27680
	s_waitcnt lgkmcnt(3)
	v_mfma_f32_32x32x16_bf16 v[80:95], v[128:131], v[172:175], v[80:95]
	ds_read_b128 v[172:175], v247 offset:27712
	s_waitcnt lgkmcnt(3)
	v_mfma_f32_32x32x16_bf16 v[80:95], v[132:135], v[176:179], v[80:95]
	ds_read_b128 v[176:179], v247 offset:27744
	s_waitcnt lgkmcnt(3)
	v_mfma_f32_32x32x16_bf16 v[48:63], v[164:167], v[136:139], v[48:63]
	ds_read_b128 v[136:139], v247 offset:32256
	s_waitcnt lgkmcnt(3)
	v_mfma_f32_32x32x16_bf16 v[48:63], v[160:163], v[140:143], v[48:63]
	ds_read_b128 v[140:143], v247 offset:32288
	s_waitcnt lgkmcnt(3)
	v_mfma_f32_32x32x16_bf16 v[48:63], v[128:131], v[172:175], v[48:63]
	ds_read_b128 v[172:175], v247 offset:32320
	s_waitcnt lgkmcnt(3)
	v_mfma_f32_32x32x16_bf16 v[48:63], v[132:135], v[176:179], v[48:63]
	ds_read_b128 v[176:179], v247 offset:32352
	s_waitcnt lgkmcnt(3)
	v_mfma_f32_32x32x16_bf16 v[16:31], v[164:167], v[136:139], v[16:31]
	s_waitcnt lgkmcnt(2)
	v_mfma_f32_32x32x16_bf16 v[16:31], v[160:163], v[140:143], v[16:31]
	s_waitcnt lgkmcnt(1)
	v_mfma_f32_32x32x16_bf16 v[16:31], v[128:131], v[172:175], v[16:31]
	s_waitcnt lgkmcnt(0)
	v_mfma_f32_32x32x16_bf16 v[16:31], v[132:135], v[176:179], v[16:31]
	s_bitcmp1_b32 s54, 0
	s_cselect_b32 s55, 0x9000, 0
	s_add_i32 s55, s55, 0
	v_add_u32_e32 v128, s55, v168
	s_waitcnt vmcnt(3)
	ds_write_b128 v128, v[152:155]
	s_waitcnt vmcnt(1)
	ds_write_b128 v128, v[156:159] offset:4608
	v_add_u32_e32 v128, s55, v244
	v_add_u32_e32 v129, 0x4800, v128
	v_add_u32_e32 v128, 0x6800, v128
	ds_write2_b64 v129, v[148:149], v[150:151] offset1:2
	s_waitcnt vmcnt(0)
	ds_write2_b64 v128, v[144:145], v[146:147] offset0:128 offset1:130
	s_waitcnt lgkmcnt(0)
	s_barrier
	s_cmp_eq_u32 s17, s54
	s_mov_b32 s55, s54
	s_cbranch_scc0 .LBB0_290
	v_mov_b32_e32 v238, 0x3727c5ac
	v_mov_b32_e32 v248, 0x2400
